# P1 in-projection epilogue (rotary tiles): rope-table loads de-serialised (3-row prefetch ring, counted vmcnt, no store drain per row)
# speedup vs baseline: 1.0192x; 1.0050x over previous
; __device__ __forceinline__ unsigned cvt_pk_bf16(float lo, float hi) { unsigned r; asm volatile("v_cvt_pk_bf16_f32 %0, %1, %2" : "=v"(r) : "v"(lo), "v"(hi)); return r; }
;     __device__ __forceinline__ void operator()(const f32x4 (&acc)[2][2][4][2], const Unit& u, int wr, int wc, int fr, int fq) const {
;     ...
;             for (int m = 0; m < 4; ++m) { const int row = row0 + ai * HALF + m * 16; bf16_t* rowp = H + (size_t)row * INC + col0;
;                 f32x4 c0 = {1.f, 1.f, 1.f, 1.f}, c1 = c0, s0 = {0.f, 0.f, 0.f, 0.f}, s1 = s0;
;                 if (ropewave && fq < 2) { const float* rp = rope + (size_t)((row0g + row) & smask) * 16;
;                     c0 = *(const f32x4*)rp; c1 = *(const f32x4*)(rp + 4); s0 = *(const f32x4*)(rp + 8); s1 = *(const f32x4*)(rp + 12);
;                     if (fq == 0) { s0 = -s0; s1 = -s1; } }
;     ...
;                     u32x4 w; w.x = cvt_pk_bf16(v0[0], v0[1]); w.y = cvt_pk_bf16(v0[2], v0[3]); w.z = cvt_pk_bf16(v1[0], v1[1]); w.w = cvt_pk_bf16(v1[2], v1[3]);
;                     *(u32x4*)(rowp + bj * HALF) = w; } }
.LBB0_171:
	s_add_i32 s11, s44, -4
	s_cmp_lt_u32 s11, 8
	s_cselect_b64 s[12:13], -1, 0
	s_and_b64 s[78:79], s[96:97], s[12:13]
	v_lshl_add_u32 v168, s42, 8, v164
	s_and_b64 s[70:71], s[78:79], s[36:37]
	v_mov_b32_e32 v156, 0
	v_mov_b32_e32 v134, 1.0
	v_mov_b32_e32 v135, 1.0
	v_mov_b32_e32 v136, 1.0
	v_mov_b32_e32 v137, 1.0
	v_mov_b32_e32 v130, 1.0
	v_mov_b32_e32 v131, 1.0
	v_mov_b32_e32 v132, 1.0
	v_mov_b32_e32 v133, 1.0
	v_mov_b32_e32 v157, 0
	v_mov_b32_e32 v158, 0
	v_mov_b32_e32 v159, 0
	v_mov_b32_e32 v154, 0
	v_mov_b32_e32 v155, 0
	v_mov_b32_e32 v152, 0
	v_mov_b32_e32 v153, 0
	s_and_saveexec_b64 s[42:43], s[70:71]
	s_cbranch_execz .LBB0_173
	v_add_u32_e32 v96, s24, v168
	v_and_b32_e32 v96, s69, v96
	v_lshlrev_b64 v[130:131], 6, v[96:97]
	v_lshl_add_u64 v[130:131], s[64:65], 0, v[130:131]
	v_mov_b32_e32 v182, v130
	v_mov_b32_e32 v183, v131
	s_mov_b32 s84, 0x2000
	s_mov_b32 s85, 0
	v_lshl_add_u64 v[178:179], v[182:183], 0, s[84:85]
	global_load_dwordx4 v[186:189], v[182:183], off
	global_load_dwordx4 v[190:193], v[182:183], off offset:16
	global_load_dwordx4 v[194:197], v[182:183], off offset:32
	global_load_dwordx4 v[210:213], v[182:183], off offset:48
	global_load_dwordx4 v[214:217], v[182:183], off offset:1024
	global_load_dwordx4 v[218:221], v[182:183], off offset:1040
	global_load_dwordx4 v[222:225], v[182:183], off offset:1056
	global_load_dwordx4 v[226:229], v[182:183], off offset:1072
	global_load_dwordx4 v[230:233], v[182:183], off offset:2048
	global_load_dwordx4 v[234:237], v[182:183], off offset:2064
	global_load_dwordx4 v[238:241], v[182:183], off offset:2080
	global_load_dwordx4 v[242:245], v[182:183], off offset:2096
	s_nop 0
	s_waitcnt vmcnt(8)
	v_mov_b32_e32 v134, v186
	v_mov_b32_e32 v135, v187
	v_mov_b32_e32 v136, v188
	v_mov_b32_e32 v137, v189
	v_mov_b32_e32 v130, v190
	v_mov_b32_e32 v131, v191
	v_mov_b32_e32 v132, v192
	v_mov_b32_e32 v133, v193
	v_mov_b32_e32 v150, v194
	v_mov_b32_e32 v151, v195
	v_mov_b32_e32 v152, v196
	v_mov_b32_e32 v153, v197
	v_mov_b32_e32 v160, v210
	v_mov_b32_e32 v161, v211
	v_mov_b32_e32 v162, v212
	v_mov_b32_e32 v163, v213
	global_load_dwordx4 v[186:189], v[182:183], off offset:3072
	global_load_dwordx4 v[190:193], v[182:183], off offset:3088
	global_load_dwordx4 v[194:197], v[182:183], off offset:3104
	global_load_dwordx4 v[210:213], v[182:183], off offset:3120
	v_xor_b32_e32 v96, 0x80000000, v153
	v_xor_b32_e32 v154, 0x80000000, v152
	v_xor_b32_e32 v155, 0x80000000, v151
	v_xor_b32_e32 v156, 0x80000000, v150
	v_xor_b32_e32 v169, 0x80000000, v163
	v_xor_b32_e32 v170, 0x80000000, v162
	v_xor_b32_e32 v171, 0x80000000, v161
	v_xor_b32_e32 v172, 0x80000000, v160
	v_cndmask_b32_e64 v156, v150, v156, s[38:39]
	v_cndmask_b32_e64 v157, v151, v155, s[38:39]
	v_cndmask_b32_e64 v158, v152, v154, s[38:39]
	v_cndmask_b32_e64 v159, v153, v96, s[38:39]
	v_cndmask_b32_e64 v154, v160, v172, s[38:39]
	v_cndmask_b32_e64 v155, v161, v171, s[38:39]
	v_cndmask_b32_e64 v152, v162, v170, s[38:39]
	v_cndmask_b32_e64 v153, v163, v169, s[38:39]

; __device__ __forceinline__ unsigned cvt_pk_bf16(float lo, float hi) { unsigned r; asm volatile("v_cvt_pk_bf16_f32 %0, %1, %2" : "=v"(r) : "v"(lo), "v"(hi)); return r; }
;     __device__ __forceinline__ void operator()(const f32x4 (&acc)[2][2][4][2], const Unit& u, int wr, int wc, int fr, int fq) const {
;     ...
;             for (int m = 0; m < 4; ++m) { const int row = row0 + ai * HALF + m * 16; bf16_t* rowp = H + (size_t)row * INC + col0;
;                 f32x4 c0 = {1.f, 1.f, 1.f, 1.f}, c1 = c0, s0 = {0.f, 0.f, 0.f, 0.f}, s1 = s0;
;                 if (ropewave && fq < 2) { const float* rp = rope + (size_t)((row0g + row) & smask) * 16;
;                     c0 = *(const f32x4*)rp; c1 = *(const f32x4*)(rp + 4); s0 = *(const f32x4*)(rp + 8); s1 = *(const f32x4*)(rp + 12);
;                     if (fq == 0) { s0 = -s0; s1 = -s1; } }
;     ...
;                     u32x4 w; w.x = cvt_pk_bf16(v0[0], v0[1]); w.y = cvt_pk_bf16(v0[2], v0[3]); w.z = cvt_pk_bf16(v1[0], v1[1]); w.w = cvt_pk_bf16(v1[2], v1[3]);
;                     *(u32x4*)(rowp + bj * HALF) = w; } }
.LBB0_181:
	v_cvt_pk_bf16_f32 v118, v118, v119
	v_cvt_pk_bf16_f32 v119, v120, v121
	v_cvt_pk_bf16_f32 v120, v114, v115
	v_cvt_pk_bf16_f32 v121, v116, v117
	global_store_dwordx4 v[124:125], v[118:121], off offset:256
	v_or_b32_e32 v134, 16, v168
	v_mov_b32_e32 v128, 0
	v_mov_b32_e32 v118, 1.0
	v_mov_b32_e32 v119, 1.0
	v_mov_b32_e32 v120, 1.0
	v_mov_b32_e32 v121, 1.0
	v_mov_b32_e32 v114, 1.0
	v_mov_b32_e32 v115, 1.0
	v_mov_b32_e32 v116, 1.0
	v_mov_b32_e32 v117, 1.0
	v_mov_b32_e32 v129, 0
	v_mov_b32_e32 v130, 0
	v_mov_b32_e32 v131, 0
	v_mov_b32_e32 v126, 0
	v_mov_b32_e32 v127, 0
	v_mov_b32_e32 v124, 0
	v_mov_b32_e32 v125, 0
	s_and_saveexec_b64 s[78:79], s[70:71]
	s_cbranch_execz .LBB0_183
	v_add_u32_e32 v96, s24, v134
	v_and_b32_e32 v96, s69, v96
	v_lshlrev_b64 v[114:115], 6, v[96:97]
	v_lshl_add_u64 v[114:115], s[64:65], 0, v[114:115]
	s_nop 0
	s_waitcnt vmcnt(10)
	v_mov_b32_e32 v118, v214
	v_mov_b32_e32 v119, v215
	v_mov_b32_e32 v120, v216
	v_mov_b32_e32 v121, v217
	v_mov_b32_e32 v114, v218
	v_mov_b32_e32 v115, v219
	v_mov_b32_e32 v116, v220
	v_mov_b32_e32 v117, v221
	v_mov_b32_e32 v124, v222
	v_mov_b32_e32 v125, v223
	v_mov_b32_e32 v126, v224
	v_mov_b32_e32 v127, v225
	v_mov_b32_e32 v152, v226
	v_mov_b32_e32 v153, v227
	v_mov_b32_e32 v154, v228
	v_mov_b32_e32 v155, v229
	global_load_dwordx4 v[214:217], v[178:179], off
	global_load_dwordx4 v[218:221], v[178:179], off offset:16
	global_load_dwordx4 v[222:225], v[178:179], off offset:32
	global_load_dwordx4 v[226:229], v[178:179], off offset:48
	v_xor_b32_e32 v96, 0x80000000, v127
	v_xor_b32_e32 v130, 0x80000000, v126
	v_xor_b32_e32 v129, 0x80000000, v125
	v_xor_b32_e32 v128, 0x80000000, v124
	v_xor_b32_e32 v132, 0x80000000, v155
	v_xor_b32_e32 v133, 0x80000000, v154
	v_xor_b32_e32 v135, 0x80000000, v153
	v_xor_b32_e32 v136, 0x80000000, v152
	v_cndmask_b32_e64 v128, v124, v128, s[38:39]
	v_cndmask_b32_e64 v129, v125, v129, s[38:39]
	v_cndmask_b32_e64 v130, v126, v130, s[38:39]
	v_cndmask_b32_e64 v131, v127, v96, s[38:39]
	v_cndmask_b32_e64 v126, v152, v136, s[38:39]
	v_cndmask_b32_e64 v127, v153, v135, s[38:39]
	v_cndmask_b32_e64 v124, v154, v133, s[38:39]
	v_cndmask_b32_e64 v125, v155, v132, s[38:39]

; __device__ __forceinline__ unsigned cvt_pk_bf16(float lo, float hi) { unsigned r; asm volatile("v_cvt_pk_bf16_f32 %0, %1, %2" : "=v"(r) : "v"(lo), "v"(hi)); return r; }
;     __device__ __forceinline__ void operator()(const f32x4 (&acc)[2][2][4][2], const Unit& u, int wr, int wc, int fr, int fq) const {
;     ...
;             for (int m = 0; m < 4; ++m) { const int row = row0 + ai * HALF + m * 16; bf16_t* rowp = H + (size_t)row * INC + col0;
;                 f32x4 c0 = {1.f, 1.f, 1.f, 1.f}, c1 = c0, s0 = {0.f, 0.f, 0.f, 0.f}, s1 = s0;
;                 if (ropewave && fq < 2) { const float* rp = rope + (size_t)((row0g + row) & smask) * 16;
;                     c0 = *(const f32x4*)rp; c1 = *(const f32x4*)(rp + 4); s0 = *(const f32x4*)(rp + 8); s1 = *(const f32x4*)(rp + 12);
;                     if (fq == 0) { s0 = -s0; s1 = -s1; } }
;     ...
;                     u32x4 w; w.x = cvt_pk_bf16(v0[0], v0[1]); w.y = cvt_pk_bf16(v0[2], v0[3]); w.z = cvt_pk_bf16(v1[0], v1[1]); w.w = cvt_pk_bf16(v1[2], v1[3]);
;                     *(u32x4*)(rowp + bj * HALF) = w; } }
.LBB0_191:
	v_cvt_pk_bf16_f32 v102, v102, v103
	v_cvt_pk_bf16_f32 v103, v104, v105
	v_cvt_pk_bf16_f32 v104, v98, v99
	v_cvt_pk_bf16_f32 v105, v100, v101
	global_store_dwordx4 v[106:107], v[102:105], off offset:256
	v_or_b32_e32 v116, 32, v168
	v_mov_b32_e32 v110, 0
	v_mov_b32_e32 v102, 1.0
	v_mov_b32_e32 v103, 1.0
	v_mov_b32_e32 v104, 1.0
	v_mov_b32_e32 v105, 1.0
	v_mov_b32_e32 v98, 1.0
	v_mov_b32_e32 v99, 1.0
	v_mov_b32_e32 v100, 1.0
	v_mov_b32_e32 v101, 1.0
	v_mov_b32_e32 v111, 0
	v_mov_b32_e32 v112, 0
	v_mov_b32_e32 v113, 0
	v_mov_b32_e32 v108, 0
	v_mov_b32_e32 v109, 0
	v_mov_b32_e32 v106, 0
	v_mov_b32_e32 v107, 0
	s_and_saveexec_b64 s[78:79], s[70:71]
	s_cbranch_execz .LBB0_193
	v_add_u32_e32 v96, s24, v116
	v_and_b32_e32 v96, s69, v96
	v_lshlrev_b64 v[98:99], 6, v[96:97]
	v_lshl_add_u64 v[98:99], s[64:65], 0, v[98:99]
	s_nop 0
	s_waitcnt vmcnt(12)
	v_mov_b32_e32 v102, v230
	v_mov_b32_e32 v103, v231
	v_mov_b32_e32 v104, v232
	v_mov_b32_e32 v105, v233
	v_mov_b32_e32 v98, v234
	v_mov_b32_e32 v99, v235
	v_mov_b32_e32 v100, v236
	v_mov_b32_e32 v101, v237
	v_mov_b32_e32 v106, v238
	v_mov_b32_e32 v107, v239
	v_mov_b32_e32 v108, v240
	v_mov_b32_e32 v109, v241
	v_mov_b32_e32 v118, v242
	v_mov_b32_e32 v119, v243
	v_mov_b32_e32 v120, v244
	v_mov_b32_e32 v121, v245
	global_load_dwordx4 v[230:233], v[178:179], off offset:1024
	global_load_dwordx4 v[234:237], v[178:179], off offset:1040
	global_load_dwordx4 v[238:241], v[178:179], off offset:1056
	global_load_dwordx4 v[242:245], v[178:179], off offset:1072
	v_xor_b32_e32 v96, 0x80000000, v109
	v_xor_b32_e32 v112, 0x80000000, v108
	v_xor_b32_e32 v111, 0x80000000, v107
	v_xor_b32_e32 v110, 0x80000000, v106
	v_xor_b32_e32 v114, 0x80000000, v121
	v_xor_b32_e32 v115, 0x80000000, v120
	v_xor_b32_e32 v117, 0x80000000, v119
	v_xor_b32_e32 v124, 0x80000000, v118
	v_cndmask_b32_e64 v110, v106, v110, s[38:39]
	v_cndmask_b32_e64 v111, v107, v111, s[38:39]
	v_cndmask_b32_e64 v112, v108, v112, s[38:39]
	v_cndmask_b32_e64 v113, v109, v96, s[38:39]
	v_cndmask_b32_e64 v108, v118, v124, s[38:39]
	v_cndmask_b32_e64 v109, v119, v117, s[38:39]
	v_cndmask_b32_e64 v106, v120, v115, s[38:39]
	v_cndmask_b32_e64 v107, v121, v114, s[38:39]

; __device__ __forceinline__ unsigned cvt_pk_bf16(float lo, float hi) { unsigned r; asm volatile("v_cvt_pk_bf16_f32 %0, %1, %2" : "=v"(r) : "v"(lo), "v"(hi)); return r; }
;     __device__ __forceinline__ void operator()(const f32x4 (&acc)[2][2][4][2], const Unit& u, int wr, int wc, int fr, int fq) const {
;     ...
;             for (int m = 0; m < 4; ++m) { const int row = row0 + ai * HALF + m * 16; bf16_t* rowp = H + (size_t)row * INC + col0;
;                 f32x4 c0 = {1.f, 1.f, 1.f, 1.f}, c1 = c0, s0 = {0.f, 0.f, 0.f, 0.f}, s1 = s0;
;                 if (ropewave && fq < 2) { const float* rp = rope + (size_t)((row0g + row) & smask) * 16;
;                     c0 = *(const f32x4*)rp; c1 = *(const f32x4*)(rp + 4); s0 = *(const f32x4*)(rp + 8); s1 = *(const f32x4*)(rp + 12);
;                     if (fq == 0) { s0 = -s0; s1 = -s1; } }
;     ...
;                     u32x4 w; w.x = cvt_pk_bf16(v0[0], v0[1]); w.y = cvt_pk_bf16(v0[2], v0[3]); w.z = cvt_pk_bf16(v1[0], v1[1]); w.w = cvt_pk_bf16(v1[2], v1[3]);
;                     *(u32x4*)(rowp + bj * HALF) = w; } }
.LBB0_201:
	v_cvt_pk_bf16_f32 v84, v84, v85
	v_cvt_pk_bf16_f32 v85, v86, v87
	v_cvt_pk_bf16_f32 v86, v80, v81
	v_cvt_pk_bf16_f32 v87, v82, v83
	global_store_dwordx4 v[88:89], v[84:87], off offset:256
	v_or_b32_e32 v100, 48, v168
	v_mov_b32_e32 v92, 0
	v_mov_b32_e32 v84, 1.0
	v_mov_b32_e32 v85, 1.0
	v_mov_b32_e32 v86, 1.0
	v_mov_b32_e32 v87, 1.0
	v_mov_b32_e32 v80, 1.0
	v_mov_b32_e32 v81, 1.0
	v_mov_b32_e32 v82, 1.0
	v_mov_b32_e32 v83, 1.0
	v_mov_b32_e32 v93, 0
	v_mov_b32_e32 v94, 0
	v_mov_b32_e32 v95, 0
	v_mov_b32_e32 v90, 0
	v_mov_b32_e32 v91, 0
	v_mov_b32_e32 v88, 0
	v_mov_b32_e32 v89, 0
	s_and_saveexec_b64 s[78:79], s[70:71]
	s_cbranch_execz .LBB0_203
	v_add_u32_e32 v80, s24, v100
	v_and_b32_e32 v96, s69, v80
	v_lshlrev_b64 v[80:81], 6, v[96:97]
	v_lshl_add_u64 v[80:81], s[64:65], 0, v[80:81]
	s_nop 0
	s_waitcnt vmcnt(14)
	v_mov_b32_e32 v84, v186
	v_mov_b32_e32 v85, v187
	v_mov_b32_e32 v86, v188
	v_mov_b32_e32 v87, v189
	v_mov_b32_e32 v80, v190
	v_mov_b32_e32 v81, v191
	v_mov_b32_e32 v82, v192
	v_mov_b32_e32 v83, v193
	v_mov_b32_e32 v88, v194
	v_mov_b32_e32 v89, v195
	v_mov_b32_e32 v90, v196
	v_mov_b32_e32 v91, v197
	v_mov_b32_e32 v102, v210
	v_mov_b32_e32 v103, v211
	v_mov_b32_e32 v104, v212
	v_mov_b32_e32 v105, v213
	global_load_dwordx4 v[186:189], v[178:179], off offset:2048
	global_load_dwordx4 v[190:193], v[178:179], off offset:2064
	global_load_dwordx4 v[194:197], v[178:179], off offset:2080
	global_load_dwordx4 v[210:213], v[178:179], off offset:2096
	v_xor_b32_e32 v95, 0x80000000, v91
	v_xor_b32_e32 v94, 0x80000000, v90
	v_xor_b32_e32 v93, 0x80000000, v89
	v_xor_b32_e32 v92, 0x80000000, v88
	v_xor_b32_e32 v96, 0x80000000, v105
	v_xor_b32_e32 v98, 0x80000000, v104
	v_xor_b32_e32 v99, 0x80000000, v103
	v_xor_b32_e32 v101, 0x80000000, v102
	v_cndmask_b32_e64 v92, v88, v92, s[38:39]
	v_cndmask_b32_e64 v93, v89, v93, s[38:39]
	v_cndmask_b32_e64 v94, v90, v94, s[38:39]
	v_cndmask_b32_e64 v95, v91, v95, s[38:39]
	v_cndmask_b32_e64 v90, v102, v101, s[38:39]
	v_cndmask_b32_e64 v91, v103, v99, s[38:39]
	v_cndmask_b32_e64 v88, v104, v98, s[38:39]
	v_cndmask_b32_e64 v89, v105, v96, s[38:39]

; __device__ __forceinline__ unsigned cvt_pk_bf16(float lo, float hi) { unsigned r; asm volatile("v_cvt_pk_bf16_f32 %0, %1, %2" : "=v"(r) : "v"(lo), "v"(hi)); return r; }
;     __device__ __forceinline__ void operator()(const f32x4 (&acc)[2][2][4][2], const Unit& u, int wr, int wc, int fr, int fq) const {
;     ...
;             for (int m = 0; m < 4; ++m) { const int row = row0 + ai * HALF + m * 16; bf16_t* rowp = H + (size_t)row * INC + col0;
;                 f32x4 c0 = {1.f, 1.f, 1.f, 1.f}, c1 = c0, s0 = {0.f, 0.f, 0.f, 0.f}, s1 = s0;
;                 if (ropewave && fq < 2) { const float* rp = rope + (size_t)((row0g + row) & smask) * 16;
;                     c0 = *(const f32x4*)rp; c1 = *(const f32x4*)(rp + 4); s0 = *(const f32x4*)(rp + 8); s1 = *(const f32x4*)(rp + 12);
;                     if (fq == 0) { s0 = -s0; s1 = -s1; } }
;     ...
;                     u32x4 w; w.x = cvt_pk_bf16(v0[0], v0[1]); w.y = cvt_pk_bf16(v0[2], v0[3]); w.z = cvt_pk_bf16(v1[0], v1[1]); w.w = cvt_pk_bf16(v1[2], v1[3]);
;                     *(u32x4*)(rowp + bj * HALF) = w; } }
.LBB0_211:
	v_cvt_pk_bf16_f32 v68, v68, v69
	v_cvt_pk_bf16_f32 v69, v70, v71
	v_cvt_pk_bf16_f32 v70, v64, v65
	v_cvt_pk_bf16_f32 v71, v66, v67
	global_store_dwordx4 v[72:73], v[68:71], off offset:256
	v_add_u32_e32 v82, 0x80, v168
	v_mov_b32_e32 v76, 0
	v_mov_b32_e32 v68, 1.0
	v_mov_b32_e32 v69, 1.0
	v_mov_b32_e32 v70, 1.0
	v_mov_b32_e32 v71, 1.0
	v_mov_b32_e32 v64, 1.0
	v_mov_b32_e32 v65, 1.0
	v_mov_b32_e32 v66, 1.0
	v_mov_b32_e32 v67, 1.0
	v_mov_b32_e32 v77, 0
	v_mov_b32_e32 v78, 0
	v_mov_b32_e32 v79, 0
	v_mov_b32_e32 v74, 0
	v_mov_b32_e32 v75, 0
	v_mov_b32_e32 v72, 0
	v_mov_b32_e32 v73, 0
	s_and_saveexec_b64 s[78:79], s[70:71]
	s_cbranch_execz .LBB0_213
	v_add_u32_e32 v64, s24, v82
	v_and_b32_e32 v96, s69, v64
	v_lshlrev_b64 v[64:65], 6, v[96:97]
	v_lshl_add_u64 v[64:65], s[64:65], 0, v[64:65]
	s_nop 0
	s_waitcnt vmcnt(14)
	v_mov_b32_e32 v68, v214
	v_mov_b32_e32 v69, v215
	v_mov_b32_e32 v70, v216
	v_mov_b32_e32 v71, v217
	v_mov_b32_e32 v64, v218
	v_mov_b32_e32 v65, v219
	v_mov_b32_e32 v66, v220
	v_mov_b32_e32 v67, v221
	v_mov_b32_e32 v72, v222
	v_mov_b32_e32 v73, v223
	v_mov_b32_e32 v74, v224
	v_mov_b32_e32 v75, v225
	v_mov_b32_e32 v84, v226
	v_mov_b32_e32 v85, v227
	v_mov_b32_e32 v86, v228
	v_mov_b32_e32 v87, v229
	global_load_dwordx4 v[214:217], v[178:179], off offset:3072
	global_load_dwordx4 v[218:221], v[178:179], off offset:3088
	global_load_dwordx4 v[222:225], v[178:179], off offset:3104
	global_load_dwordx4 v[226:229], v[178:179], off offset:3120
	v_xor_b32_e32 v79, 0x80000000, v75
	v_xor_b32_e32 v78, 0x80000000, v74
	v_xor_b32_e32 v77, 0x80000000, v73
	v_xor_b32_e32 v76, 0x80000000, v72
	v_xor_b32_e32 v80, 0x80000000, v87
	v_xor_b32_e32 v81, 0x80000000, v86
	v_xor_b32_e32 v83, 0x80000000, v85
	v_xor_b32_e32 v88, 0x80000000, v84
	v_cndmask_b32_e64 v76, v72, v76, s[38:39]
	v_cndmask_b32_e64 v77, v73, v77, s[38:39]
	v_cndmask_b32_e64 v78, v74, v78, s[38:39]
	v_cndmask_b32_e64 v79, v75, v79, s[38:39]
	v_cndmask_b32_e64 v74, v84, v88, s[38:39]
	v_cndmask_b32_e64 v75, v85, v83, s[38:39]
	v_cndmask_b32_e64 v72, v86, v81, s[38:39]
	v_cndmask_b32_e64 v73, v87, v80, s[38:39]

; __device__ __forceinline__ unsigned cvt_pk_bf16(float lo, float hi) { unsigned r; asm volatile("v_cvt_pk_bf16_f32 %0, %1, %2" : "=v"(r) : "v"(lo), "v"(hi)); return r; }
;     __device__ __forceinline__ void operator()(const f32x4 (&acc)[2][2][4][2], const Unit& u, int wr, int wc, int fr, int fq) const {
;     ...
;             for (int m = 0; m < 4; ++m) { const int row = row0 + ai * HALF + m * 16; bf16_t* rowp = H + (size_t)row * INC + col0;
;                 f32x4 c0 = {1.f, 1.f, 1.f, 1.f}, c1 = c0, s0 = {0.f, 0.f, 0.f, 0.f}, s1 = s0;
;                 if (ropewave && fq < 2) { const float* rp = rope + (size_t)((row0g + row) & smask) * 16;
;                     c0 = *(const f32x4*)rp; c1 = *(const f32x4*)(rp + 4); s0 = *(const f32x4*)(rp + 8); s1 = *(const f32x4*)(rp + 12);
;                     if (fq == 0) { s0 = -s0; s1 = -s1; } }
;     ...
;                     u32x4 w; w.x = cvt_pk_bf16(v0[0], v0[1]); w.y = cvt_pk_bf16(v0[2], v0[3]); w.z = cvt_pk_bf16(v1[0], v1[1]); w.w = cvt_pk_bf16(v1[2], v1[3]);
;                     *(u32x4*)(rowp + bj * HALF) = w; } }
.LBB0_221:
	v_cvt_pk_bf16_f32 v52, v52, v53
	v_cvt_pk_bf16_f32 v53, v54, v55
	v_cvt_pk_bf16_f32 v54, v48, v49
	v_cvt_pk_bf16_f32 v55, v50, v51
	global_store_dwordx4 v[56:57], v[52:55], off offset:256
	v_add_u32_e32 v66, 0x90, v168
	v_mov_b32_e32 v60, 0
	v_mov_b32_e32 v52, 1.0
	v_mov_b32_e32 v53, 1.0
	v_mov_b32_e32 v54, 1.0
	v_mov_b32_e32 v55, 1.0
	v_mov_b32_e32 v48, 1.0
	v_mov_b32_e32 v49, 1.0
	v_mov_b32_e32 v50, 1.0
	v_mov_b32_e32 v51, 1.0
	v_mov_b32_e32 v61, 0
	v_mov_b32_e32 v62, 0
	v_mov_b32_e32 v63, 0
	v_mov_b32_e32 v58, 0
	v_mov_b32_e32 v59, 0
	v_mov_b32_e32 v56, 0
	v_mov_b32_e32 v57, 0
	s_and_saveexec_b64 s[78:79], s[70:71]
	s_cbranch_execz .LBB0_223
	v_add_u32_e32 v48, s24, v66
	v_and_b32_e32 v96, s69, v48
	v_lshlrev_b64 v[48:49], 6, v[96:97]
	v_lshl_add_u64 v[48:49], s[64:65], 0, v[48:49]
	s_nop 0
	s_waitcnt vmcnt(14)
	v_mov_b32_e32 v52, v230
	v_mov_b32_e32 v53, v231
	v_mov_b32_e32 v54, v232
	v_mov_b32_e32 v55, v233
	v_mov_b32_e32 v48, v234
	v_mov_b32_e32 v49, v235
	v_mov_b32_e32 v50, v236
	v_mov_b32_e32 v51, v237
	v_mov_b32_e32 v56, v238
	v_mov_b32_e32 v57, v239
	v_mov_b32_e32 v58, v240
	v_mov_b32_e32 v59, v241
	v_mov_b32_e32 v68, v242
	v_mov_b32_e32 v69, v243
	v_mov_b32_e32 v70, v244
	v_mov_b32_e32 v71, v245
	v_xor_b32_e32 v63, 0x80000000, v59
	v_xor_b32_e32 v62, 0x80000000, v58
	v_xor_b32_e32 v61, 0x80000000, v57
	v_xor_b32_e32 v60, 0x80000000, v56
	v_xor_b32_e32 v64, 0x80000000, v71
	v_xor_b32_e32 v65, 0x80000000, v70
	v_xor_b32_e32 v67, 0x80000000, v69
	v_xor_b32_e32 v72, 0x80000000, v68
	v_cndmask_b32_e64 v60, v56, v60, s[38:39]
	v_cndmask_b32_e64 v61, v57, v61, s[38:39]
	v_cndmask_b32_e64 v62, v58, v62, s[38:39]
	v_cndmask_b32_e64 v63, v59, v63, s[38:39]
	v_cndmask_b32_e64 v58, v68, v72, s[38:39]
	v_cndmask_b32_e64 v59, v69, v67, s[38:39]
	v_cndmask_b32_e64 v56, v70, v65, s[38:39]
	v_cndmask_b32_e64 v57, v71, v64, s[38:39]

; __device__ __forceinline__ unsigned cvt_pk_bf16(float lo, float hi) { unsigned r; asm volatile("v_cvt_pk_bf16_f32 %0, %1, %2" : "=v"(r) : "v"(lo), "v"(hi)); return r; }
;     __device__ __forceinline__ void operator()(const f32x4 (&acc)[2][2][4][2], const Unit& u, int wr, int wc, int fr, int fq) const {
;     ...
;             for (int m = 0; m < 4; ++m) { const int row = row0 + ai * HALF + m * 16; bf16_t* rowp = H + (size_t)row * INC + col0;
;                 f32x4 c0 = {1.f, 1.f, 1.f, 1.f}, c1 = c0, s0 = {0.f, 0.f, 0.f, 0.f}, s1 = s0;
;                 if (ropewave && fq < 2) { const float* rp = rope + (size_t)((row0g + row) & smask) * 16;
;                     c0 = *(const f32x4*)rp; c1 = *(const f32x4*)(rp + 4); s0 = *(const f32x4*)(rp + 8); s1 = *(const f32x4*)(rp + 12);
;                     if (fq == 0) { s0 = -s0; s1 = -s1; } }
;     ...
;                     u32x4 w; w.x = cvt_pk_bf16(v0[0], v0[1]); w.y = cvt_pk_bf16(v0[2], v0[3]); w.z = cvt_pk_bf16(v1[0], v1[1]); w.w = cvt_pk_bf16(v1[2], v1[3]);
;                     *(u32x4*)(rowp + bj * HALF) = w; } }
.LBB0_231:
	v_cvt_pk_bf16_f32 v36, v36, v37
	v_cvt_pk_bf16_f32 v37, v38, v39
	v_cvt_pk_bf16_f32 v38, v32, v33
	v_cvt_pk_bf16_f32 v39, v34, v35
	global_store_dwordx4 v[40:41], v[36:39], off offset:256
	v_add_u32_e32 v50, 0xa0, v168
	v_mov_b32_e32 v44, 0
	v_mov_b32_e32 v36, 1.0
	v_mov_b32_e32 v37, 1.0
	v_mov_b32_e32 v38, 1.0
	v_mov_b32_e32 v39, 1.0
	v_mov_b32_e32 v32, 1.0
	v_mov_b32_e32 v33, 1.0
	v_mov_b32_e32 v34, 1.0
	v_mov_b32_e32 v35, 1.0
	v_mov_b32_e32 v45, 0
	v_mov_b32_e32 v46, 0
	v_mov_b32_e32 v47, 0
	v_mov_b32_e32 v42, 0
	v_mov_b32_e32 v43, 0
	v_mov_b32_e32 v40, 0
	v_mov_b32_e32 v41, 0
	s_and_saveexec_b64 s[78:79], s[70:71]
	s_cbranch_execz .LBB0_233
	v_add_u32_e32 v32, s24, v50
	v_and_b32_e32 v96, s69, v32
	v_lshlrev_b64 v[32:33], 6, v[96:97]
	v_lshl_add_u64 v[32:33], s[64:65], 0, v[32:33]
	s_nop 0
	s_waitcnt vmcnt(10)
	v_mov_b32_e32 v36, v186
	v_mov_b32_e32 v37, v187
	v_mov_b32_e32 v38, v188
	v_mov_b32_e32 v39, v189
	v_mov_b32_e32 v32, v190
	v_mov_b32_e32 v33, v191
	v_mov_b32_e32 v34, v192
	v_mov_b32_e32 v35, v193
	v_mov_b32_e32 v40, v194
	v_mov_b32_e32 v41, v195
	v_mov_b32_e32 v42, v196
	v_mov_b32_e32 v43, v197
	v_mov_b32_e32 v52, v210
	v_mov_b32_e32 v53, v211
	v_mov_b32_e32 v54, v212
	v_mov_b32_e32 v55, v213
	v_xor_b32_e32 v47, 0x80000000, v43
	v_xor_b32_e32 v46, 0x80000000, v42
	v_xor_b32_e32 v45, 0x80000000, v41
	v_xor_b32_e32 v44, 0x80000000, v40
	v_xor_b32_e32 v48, 0x80000000, v55
	v_xor_b32_e32 v49, 0x80000000, v54
	v_xor_b32_e32 v51, 0x80000000, v53
	v_xor_b32_e32 v56, 0x80000000, v52
	v_cndmask_b32_e64 v44, v40, v44, s[38:39]
	v_cndmask_b32_e64 v45, v41, v45, s[38:39]
	v_cndmask_b32_e64 v46, v42, v46, s[38:39]
	v_cndmask_b32_e64 v47, v43, v47, s[38:39]
	v_cndmask_b32_e64 v42, v52, v56, s[38:39]
	v_cndmask_b32_e64 v43, v53, v51, s[38:39]
	v_cndmask_b32_e64 v40, v54, v49, s[38:39]
	v_cndmask_b32_e64 v41, v55, v48, s[38:39]

; __device__ __forceinline__ unsigned cvt_pk_bf16(float lo, float hi) { unsigned r; asm volatile("v_cvt_pk_bf16_f32 %0, %1, %2" : "=v"(r) : "v"(lo), "v"(hi)); return r; }
;     __device__ __forceinline__ void operator()(const f32x4 (&acc)[2][2][4][2], const Unit& u, int wr, int wc, int fr, int fq) const {
;     ...
;             for (int m = 0; m < 4; ++m) { const int row = row0 + ai * HALF + m * 16; bf16_t* rowp = H + (size_t)row * INC + col0;
;                 f32x4 c0 = {1.f, 1.f, 1.f, 1.f}, c1 = c0, s0 = {0.f, 0.f, 0.f, 0.f}, s1 = s0;
;                 if (ropewave && fq < 2) { const float* rp = rope + (size_t)((row0g + row) & smask) * 16;
;                     c0 = *(const f32x4*)rp; c1 = *(const f32x4*)(rp + 4); s0 = *(const f32x4*)(rp + 8); s1 = *(const f32x4*)(rp + 12);
;                     if (fq == 0) { s0 = -s0; s1 = -s1; } }
;     ...
;                     u32x4 w; w.x = cvt_pk_bf16(v0[0], v0[1]); w.y = cvt_pk_bf16(v0[2], v0[3]); w.z = cvt_pk_bf16(v1[0], v1[1]); w.w = cvt_pk_bf16(v1[2], v1[3]);
;                     *(u32x4*)(rowp + bj * HALF) = w; } }
.LBB0_241:
	v_cvt_pk_bf16_f32 v20, v20, v21
	v_cvt_pk_bf16_f32 v21, v22, v23
	v_cvt_pk_bf16_f32 v22, v16, v17
	v_cvt_pk_bf16_f32 v23, v18, v19
	global_store_dwordx4 v[24:25], v[20:23], off offset:256
	v_add_u32_e32 v34, 0xb0, v168
	v_mov_b32_e32 v28, 0
	v_mov_b32_e32 v20, 1.0
	v_mov_b32_e32 v21, 1.0
	v_mov_b32_e32 v22, 1.0
	v_mov_b32_e32 v23, 1.0
	v_mov_b32_e32 v16, 1.0
	v_mov_b32_e32 v17, 1.0
	v_mov_b32_e32 v18, 1.0
	v_mov_b32_e32 v19, 1.0
	v_mov_b32_e32 v29, 0
	v_mov_b32_e32 v30, 0
	v_mov_b32_e32 v31, 0
	v_mov_b32_e32 v26, 0
	v_mov_b32_e32 v27, 0
	v_mov_b32_e32 v24, 0
	v_mov_b32_e32 v25, 0
	s_and_saveexec_b64 s[78:79], s[70:71]
	s_cbranch_execz .LBB0_243
	v_add_u32_e32 v16, s24, v34
	v_and_b32_e32 v96, s69, v16
	v_lshlrev_b64 v[16:17], 6, v[96:97]
	v_lshl_add_u64 v[16:17], s[64:65], 0, v[16:17]
	s_nop 0
	s_waitcnt vmcnt(6)
	v_mov_b32_e32 v20, v214
	v_mov_b32_e32 v21, v215
	v_mov_b32_e32 v22, v216
	v_mov_b32_e32 v23, v217
	v_mov_b32_e32 v16, v218
	v_mov_b32_e32 v17, v219
	v_mov_b32_e32 v18, v220
	v_mov_b32_e32 v19, v221
	v_mov_b32_e32 v24, v222
	v_mov_b32_e32 v25, v223
	v_mov_b32_e32 v26, v224
	v_mov_b32_e32 v27, v225
	v_mov_b32_e32 v36, v226
	v_mov_b32_e32 v37, v227
	v_mov_b32_e32 v38, v228
	v_mov_b32_e32 v39, v229
	v_xor_b32_e32 v31, 0x80000000, v27
	v_xor_b32_e32 v30, 0x80000000, v26
	v_xor_b32_e32 v29, 0x80000000, v25
	v_xor_b32_e32 v28, 0x80000000, v24
	v_xor_b32_e32 v32, 0x80000000, v39
	v_xor_b32_e32 v33, 0x80000000, v38
	v_xor_b32_e32 v35, 0x80000000, v37
	v_xor_b32_e32 v40, 0x80000000, v36
	v_cndmask_b32_e64 v28, v24, v28, s[38:39]
	v_cndmask_b32_e64 v29, v25, v29, s[38:39]
	v_cndmask_b32_e64 v30, v26, v30, s[38:39]
	v_cndmask_b32_e64 v31, v27, v31, s[38:39]
	v_cndmask_b32_e64 v26, v36, v40, s[38:39]
	v_cndmask_b32_e64 v27, v37, v35, s[38:39]
	v_cndmask_b32_e64 v24, v38, v33, s[38:39]
	v_cndmask_b32_e64 v25, v39, v32, s[38:39]
